# dk=64 attention: waves 4-7 run a rotated tile body (PV of tile t-1, then QK+softmax of tile t) so their MFMA and VALU phases complement waves 0-3; 5-slot K/V ring; far exit branches made local
# baseline (speedup 1.0000x reference)
; DI CvtJob cvt_decode(KParams P, int tile) {
;   constexpr int NJ = 11;
;   const int jK[NJ]  = {2048, 768, 512, 2048, 2048, 256, 2048, 2048, 8192, 2048, 8192};
;   const int jNT[NJ] = {69, 24, 32, 32, 64, 64, 32, 128, 32, 128, 32};
;   int j = 0, idx = tile;
; #pragma unroll
;   for (int jj = 0; jj < NJ - 1; ++jj) { const int cnt = (jK[jj] / 128) * jNT[jj]; if (j == jj && idx >= cnt) { idx -= cnt; j = jj + 1; } }
;   int K = 2048;
;   switch (j) { case 1: K = 768; break; case 2: K = 512; break; case 5: K = 256; break; case 8: case 10: K = 8192; break; default: break; }
;   const int nkt = K / 128, kt = idx % nkt, ntile = idx / nkt, k0 = kt * 128, n0 = ntile * 64;
; __global__ void __launch_bounds__(512, 2) fwd_kernel(Params Parg) {
;     ...
;   for (int st2 = 2 * step_lo; st2 < 2 * step_hi; ++st2) {
;     const int st = st2 >> 1;
;     if ((st2 & 1) && !((REPEAT_MASK >> st) & 1)) continue;
.LBB0_5:
	s_waitcnt lgkmcnt(0)
	v_writelane_b32 v251, s8, 3
	s_nop 1
	v_writelane_b32 v251, s9, 4
	s_or_b64 exec, exec, s[0:1]
	s_lshl_b32 s66, s62, 1
	s_lshl_b32 s67, s63, 1
	s_cmp_ge_i32 s66, s67
	s_cbranch_scc0 .Lgo0
	s_endpgm
.Lgo0:
	v_readlane_b32 s12, v251, 0
	s_lshl_b32 s0, s12, 3
	s_add_u32 s68, s64, 0x710
	v_writelane_b32 v251, s0, 5
	s_addc_u32 s69, s65, 0
	s_lshl_b32 s0, s12, 9
	s_cmpk_lt_i32 s12, 0x100
	v_writelane_b32 v251, s0, 6
	s_cselect_b64 s[0:1], -1, 0
	v_writelane_b32 v251, s0, 7
	s_cmpk_gt_i32 s12, 0x44f
	s_mov_b32 s74, 0x3b000000
	v_writelane_b32 v251, s1, 8
	s_cselect_b64 s[0:1], -1, 0
	s_cmpk_lt_i32 s12, 0x450
	v_cndmask_b32_e64 v1, 0, 1, s[0:1]
	s_cselect_b64 s[0:1], -1, 0
	s_and_b64 s[4:5], s[0:1], exec
	s_cselect_b32 s3, 0, 0xfffffbb0
	s_add_i32 s3, s3, s12
	s_cmpk_lt_i32 s3, 0x90
	s_cselect_b64 s[4:5], -1, 0
	s_or_b64 s[0:1], s[0:1], s[4:5]
	s_and_b64 s[4:5], s[0:1], exec
	s_cselect_b32 s4, 0, 0xffffff70
	s_add_i32 s3, s4, s3
	s_cmpk_lt_i32 s3, 0x80
	s_cselect_b64 s[4:5], -1, 0
	s_and_b64 s[6:7], s[4:5], exec
	s_cselect_b32 s8, 2, 3
	s_or_b64 s[4:5], s[0:1], s[4:5]
	s_and_b64 s[6:7], s[4:5], exec
	s_cselect_b32 s6, 0, 0xffffff80
	s_add_i32 s6, s6, s3
	s_and_b64 s[0:1], s[0:1], exec
	v_readfirstlane_b32 s0, v1
	s_cselect_b32 s3, s0, s8
	s_cmpk_lt_i32 s6, 0x200
	s_cselect_b64 s[0:1], -1, 0
	s_or_b64 s[0:1], s[4:5], s[0:1]
	s_and_b64 s[4:5], s[0:1], exec
	s_cselect_b32 s4, 0, 0xfffffe00
	s_add_i32 s8, s4, s6
	s_cmpk_lt_i32 s8, 0x400
	s_cselect_b64 s[4:5], -1, 0
	s_and_b64 s[6:7], s[4:5], exec
	s_cselect_b32 s9, 4, 5
	s_or_b64 s[4:5], s[0:1], s[4:5]
	s_and_b64 s[6:7], s[4:5], exec
	s_cselect_b32 s6, 0, 0xfffffc00
	s_add_i32 s6, s6, s8
	s_and_b64 s[0:1], s[0:1], exec
	s_cselect_b32 s3, s3, s9
	s_cmpk_lt_i32 s6, 0x80
	s_cselect_b64 s[0:1], -1, 0
	s_or_b64 s[0:1], s[4:5], s[0:1]
	s_and_b64 s[4:5], s[0:1], exec
	s_cselect_b32 s4, 0, 0xffffff80
	s_add_i32 s8, s4, s6
	s_cmpk_lt_i32 s8, 0x200
	s_cselect_b64 s[4:5], -1, 0
	s_and_b64 s[6:7], s[4:5], exec
	s_cselect_b32 s9, 6, 7
	s_or_b64 s[4:5], s[0:1], s[4:5]
	s_and_b64 s[6:7], s[4:5], exec
	s_cselect_b32 s6, 0, 0xfffffe00
	s_add_i32 s6, s6, s8
	s_and_b64 s[0:1], s[0:1], exec
	s_cselect_b32 s3, s3, s9
	s_cmpk_lt_i32 s6, 0x800
	s_cselect_b64 s[0:1], -1, 0
	s_or_b64 s[0:1], s[4:5], s[0:1]
	s_and_b64 s[4:5], s[0:1], exec
	s_cselect_b32 s4, 0, 0xfffff800
	s_add_i32 s8, s4, s6
	s_cmpk_lt_i32 s8, 0x800
	s_cselect_b64 s[4:5], -1, 0
	s_and_b64 s[6:7], s[4:5], exec
	s_cselect_b32 s9, 8, 9
	s_or_b64 s[4:5], s[0:1], s[4:5]
	s_and_b64 s[6:7], s[4:5], exec
	s_cselect_b32 s6, 0, 0xfffff800
	s_add_i32 s6, s6, s8
	s_and_b64 s[0:1], s[0:1], exec
	s_cselect_b32 s3, s3, s9
	s_cmpk_lt_i32 s6, 0x800
	s_cselect_b64 s[0:1], -1, 0
	s_or_b64 s[0:1], s[4:5], s[0:1]
	s_and_b64 s[4:5], s[0:1], exec
	s_cselect_b32 s4, 0, 0xfffff800
	s_add_i32 s13, s4, s6
	s_and_b64 s[0:1], s[0:1], exec
	s_cselect_b32 s0, s3, 10
	v_writelane_b32 v251, s0, 9
	s_ashr_i32 s0, s12, 31
	v_writelane_b32 v251, s0, 10
	s_lshr_b32 s0, s0, 29
	s_add_i32 s0, s12, s0
	s_ashr_i32 s1, s0, 3
	s_and_b32 s0, s0, -8
	s_sub_i32 s0, s12, s0
	v_writelane_b32 v251, s1, 11
	s_cmpk_gt_u32 s12, 0x7f
	v_writelane_b32 v251, s0, 12
	s_cselect_b64 s[0:1], -1, 0
	s_cmpk_lt_i32 s12, 0xe2f0
	s_cselect_b64 s[4:5], -1, 0
	s_and_b64 s[6:7], s[4:5], exec
	s_cselect_b32 s3, 0, 0xfffffbb0
	s_add_i32 s3, s12, s3
	s_cmpk_lt_i32 s12, 0xc80
	s_cselect_b64 s[6:7], -1, 0
	v_writelane_b32 v251, s6, 13
	s_cmpk_gt_i32 s12, 0xe2ef
	v_mbcnt_lo_u32_b32 v2, -1, 0
	v_writelane_b32 v251, s7, 14
	s_cselect_b64 s[6:7], -1, 0
	s_addk_i32 s3, 0x2160
	s_cmpk_lt_i32 s3, 0x90
	v_cndmask_b32_e64 v1, 0, 1, s[6:7]
	s_cselect_b64 s[6:7], -1, 0
	s_or_b64 s[4:5], s[4:5], s[6:7]
	s_and_b64 s[6:7], s[4:5], exec
	s_cselect_b32 s6, 0, 0xffffff70
	s_add_i32 s3, s6, s3
	s_cmpk_lt_i32 s3, 0x80
	s_cselect_b64 s[6:7], -1, 0
	s_and_b64 s[8:9], s[6:7], exec
	s_cselect_b32 s10, 2, 3
	s_or_b64 s[6:7], s[4:5], s[6:7]
	s_and_b64 s[8:9], s[6:7], exec
	s_cselect_b32 s8, 0, 0xffffff80
	s_add_i32 s8, s8, s3
	s_and_b64 s[4:5], s[4:5], exec
	v_readfirstlane_b32 s3, v1
	s_cselect_b32 s3, s3, s10
	s_cmpk_lt_i32 s8, 0x200
	s_cselect_b64 s[4:5], -1, 0
	s_or_b64 s[4:5], s[6:7], s[4:5]
	s_and_b64 s[6:7], s[4:5], exec
	s_cselect_b32 s6, 0, 0xfffffe00
	s_add_i32 s10, s6, s8
	s_cmpk_lt_i32 s10, 0x400
	s_cselect_b64 s[6:7], -1, 0
	s_and_b64 s[8:9], s[6:7], exec
	s_cselect_b32 s11, 4, 5
	s_or_b64 s[6:7], s[4:5], s[6:7]
	s_and_b64 s[8:9], s[6:7], exec
	s_cselect_b32 s8, 0, 0xfffffc00
	s_add_i32 s8, s8, s10
	s_and_b64 s[4:5], s[4:5], exec
	s_cselect_b32 s3, s3, s11
	s_cmpk_lt_i32 s8, 0x80
	s_cselect_b64 s[4:5], -1, 0
	s_or_b64 s[4:5], s[6:7], s[4:5]
	s_and_b64 s[6:7], s[4:5], exec
	s_cselect_b32 s6, 0, 0xffffff80
	s_add_i32 s10, s6, s8
	s_cmpk_lt_i32 s10, 0x200
	s_cselect_b64 s[6:7], -1, 0
	s_and_b64 s[8:9], s[6:7], exec
	s_cselect_b32 s11, 6, 7
	s_or_b64 s[6:7], s[4:5], s[6:7]
	s_and_b64 s[8:9], s[6:7], exec
	s_cselect_b32 s8, 0, 0xfffffe00
	s_add_i32 s8, s8, s10
	s_and_b64 s[4:5], s[4:5], exec
	s_cselect_b32 s3, s3, s11
	s_cmpk_lt_i32 s8, 0x800
	s_cselect_b64 s[4:5], -1, 0
	s_or_b64 s[4:5], s[6:7], s[4:5]
	s_and_b64 s[6:7], s[4:5], exec
	s_cselect_b32 s6, 0, 0xfffff800
	s_add_i32 s10, s6, s8
	s_cmpk_lt_i32 s10, 0x800
	s_cselect_b64 s[6:7], -1, 0
	s_and_b64 s[8:9], s[6:7], exec
	s_cselect_b32 s11, 8, 9
	s_or_b64 s[6:7], s[4:5], s[6:7]
	s_and_b64 s[8:9], s[6:7], exec
	s_cselect_b32 s8, 0, 0xfffff800
	s_add_i32 s8, s8, s10
	s_and_b64 s[4:5], s[4:5], exec
	s_cselect_b32 s3, s3, s11
	s_cmpk_lt_i32 s8, 0x800
	s_cselect_b64 s[4:5], -1, 0
	s_or_b64 s[4:5], s[6:7], s[4:5]
	s_and_b64 s[6:7], s[4:5], exec
	s_cselect_b32 s6, 0, 0xfffff800
	s_add_i32 s6, s6, s8
	s_and_b64 s[4:5], s[4:5], exec
	s_cselect_b32 s3, s3, 10
	s_cmpk_lt_i32 s62, 0x3e9
	v_writelane_b32 v251, s3, 15
	s_cselect_b64 s[4:5], -1, 0
	v_writelane_b32 v251, s4, 16
	v_lshrrev_b32_e32 v1, 20, v0
	v_lshrrev_b32_e32 v0, 10, v0
	v_writelane_b32 v251, s5, 17
	s_load_dwordx2 s[4:5], s[64:65], 0x148
	v_or_b32_e32 v0, v0, v1
	v_mbcnt_hi_u32_b32 v191, -1, v2
	v_mov_b32_e32 v1, 0
	s_mov_b32 s76, 0x6dc9c883
	s_waitcnt lgkmcnt(0)
; __device__ __forceinline__ unsigned xb_ld(unsigned* p)              { return __hip_atomic_load(p, __ATOMIC_RELAXED, __HIP_MEMORY_SCOPE_AGENT); }
; __device__ __forceinline__ void xcd_barrier_complete(unsigned* bar, unsigned x, unsigned& nloc, unsigned& nx) {
;     const unsigned G = gridDim.x * gridDim.y * gridDim.z;
;     unsigned sum, cnt, mine, sp = 0u;
;     for (;;) {
;         sum = 0u; cnt = 0u; mine = 0u;
; #pragma unroll
;         for (unsigned j = 0; j < 16; ++j) { const unsigned c = xb_ld(&bar[XB_XCNT(j)]); sum += c; cnt += (c > 0u) ? 1u : 0u; mine = (j == x) ? c : mine; }
;         if (sum == G) break;
;         __builtin_amdgcn_s_sleep(1);
;         if ((++sp & 255u) == 0u) { if (xb_ld(&bar[XB_TMO])) break; if (sp > XB_SPIN_CAP) { atomicAdd(&bar[XB_TMO], 1u); break; } }
;     }
;     nloc = mine > 0u ? mine : 1u; nx = cnt > 0u ? cnt : 1u;
; }
	s_add_u32 s8, s4, 0x200
	s_addc_u32 s9, s5, 0
	v_writelane_b32 v251, s8, 18
	v_and_b32_e32 v2, 64, v191
	s_movk_i32 s34, 0xff00
	v_writelane_b32 v251, s9, 19
	s_add_u32 s8, s4, 0x1000
	s_addc_u32 s9, s5, 0
	v_writelane_b32 v251, s8, 20
	v_mov_b32_e32 v162, 0x358637bd
	v_mov_b32_e32 v186, 0x3727c5ac
	v_writelane_b32 v251, s9, 21
	s_add_u32 s8, s4, 0x1100
	s_addc_u32 s9, s5, 0
	s_add_u32 s70, s4, 0x1200
	s_addc_u32 s71, s5, 0
	s_add_u32 s72, s4, 0x1300
	s_addc_u32 s73, s5, 0
	v_writelane_b32 v251, s8, 22
	s_cmp_eq_u32 s2, 15
	s_mov_b32 s75, 0x3aaaaaab
	v_writelane_b32 v251, s9, 23
	s_cselect_b64 s[8:9], -1, 0
	v_writelane_b32 v251, s8, 24
	s_cmp_eq_u32 s2, 14
	s_mov_b32 s77, 0x3fc45f30
	v_writelane_b32 v251, s9, 25
	s_cselect_b64 s[8:9], -1, 0
	v_writelane_b32 v251, s8, 26
	s_cmp_eq_u32 s2, 13
	v_mov_b32_e32 v187, 0x3ecc95a3
	v_writelane_b32 v251, s9, 27
	s_cselect_b64 s[8:9], -1, 0
	v_writelane_b32 v251, s8, 28
	s_cmp_eq_u32 s2, 12
	v_mov_b32_e32 v188, 0x3e2aaaab
	v_writelane_b32 v251, s9, 29
	s_cselect_b64 s[8:9], -1, 0
	v_writelane_b32 v251, s8, 30
	s_cmp_eq_u32 s2, 11
	v_mov_b32_e32 v189, 0x260
	v_writelane_b32 v251, s9, 31
	s_cselect_b64 s[8:9], -1, 0
	v_writelane_b32 v251, s8, 32
	s_cmp_eq_u32 s2, 10
	v_mov_b32_e32 v190, 1
	v_writelane_b32 v251, s9, 33
	s_cselect_b64 s[8:9], -1, 0
	v_writelane_b32 v251, s8, 34
	s_cmp_eq_u32 s2, 9
	v_add_u32_e32 v192, 64, v2
	v_writelane_b32 v251, s9, 35
	s_cselect_b64 s[8:9], -1, 0
	v_writelane_b32 v251, s8, 36
	s_cmp_eq_u32 s2, 8
	v_xor_b32_e32 v193, 32, v191
	v_writelane_b32 v251, s9, 37
	s_cselect_b64 s[8:9], -1, 0
	v_writelane_b32 v251, s8, 38
	s_cmp_eq_u32 s2, 7
	v_xor_b32_e32 v194, 16, v191
	v_writelane_b32 v251, s9, 39
	s_cselect_b64 s[8:9], -1, 0
	v_writelane_b32 v251, s8, 40
	s_cmp_eq_u32 s2, 6
	v_xor_b32_e32 v195, 8, v191
	v_writelane_b32 v251, s9, 41
	s_cselect_b64 s[8:9], -1, 0
	v_writelane_b32 v251, s8, 42
	s_cmp_eq_u32 s2, 5
	v_xor_b32_e32 v196, 4, v191
	v_writelane_b32 v251, s9, 43
	s_cselect_b64 s[8:9], -1, 0
	v_writelane_b32 v251, s8, 44
	s_cmp_eq_u32 s2, 4
	v_xor_b32_e32 v197, 2, v191
	v_writelane_b32 v251, s9, 45
	s_cselect_b64 s[8:9], -1, 0
	v_writelane_b32 v251, s8, 46
	s_cmp_eq_u32 s2, 3
	v_xor_b32_e32 v198, 1, v191
	v_writelane_b32 v251, s9, 47
	s_cselect_b64 s[8:9], -1, 0
	v_writelane_b32 v251, s8, 48
	s_cmp_eq_u32 s2, 2
	v_mov_b32_e32 v199, 4
	v_writelane_b32 v251, s9, 49
	s_cselect_b64 s[8:9], -1, 0
	v_writelane_b32 v251, s8, 50
	s_cmp_eq_u32 s2, 1
	v_mov_b32_e32 v200, 0xffffff80
	v_writelane_b32 v251, s9, 51
	s_cselect_b64 s[8:9], -1, 0
	v_writelane_b32 v251, s8, 52
	s_cmp_eq_u32 s2, 0
	v_mov_b32_e32 v201, 0xff800000
	v_writelane_b32 v251, s9, 53
	s_cselect_b64 s[8:9], -1, 0
	s_lshl_b32 s2, s2, 8
	s_add_u32 s2, s4, s2
	v_writelane_b32 v251, s8, 54
	s_addc_u32 s3, s5, 0
	v_mov_b32_e32 v164, 0x3f317218
	v_writelane_b32 v251, s9, 55
	s_add_u32 s8, s2, 0x1400
	s_addc_u32 s9, s3, 0
	v_writelane_b32 v251, s8, 56
	s_add_u32 s2, s2, 0x2400
	s_addc_u32 s3, s3, 0
	v_writelane_b32 v251, s9, 57
	v_writelane_b32 v251, s2, 58
	v_mov_b32_e32 v202, 0x7f800000
	v_mov_b32_e32 v203, 0x7fc00000
	v_writelane_b32 v251, s3, 59
	s_add_u32 s2, s4, 0x3400
	s_addc_u32 s3, s5, 0
	v_writelane_b32 v251, s2, 60
	v_mov_b32_e32 v228, v1
	v_mov_b32_e32 v229, v1
	v_writelane_b32 v251, s3, 61
	s_movk_i32 s2, 0x3ff
	v_and_or_b32 v0, v0, s2, v163
	s_add_u32 s2, s4, 0x3500
	s_addc_u32 s3, s5, 0
	s_xor_b64 s[0:1], s[0:1], -1
	v_writelane_b32 v250, s0, 0
	v_writelane_b32 v251, s2, 62
	s_movk_i32 s78, 0x4000
	v_writelane_b32 v250, s1, 1
	s_ashr_i32 s0, s13, 31
	v_writelane_b32 v250, s0, 2
	v_writelane_b32 v250, s13, 3
	s_abs_i32 s0, s13
	v_writelane_b32 v250, s0, 4
	s_ashr_i32 s0, s6, 31
	v_writelane_b32 v250, s0, 5
	v_writelane_b32 v250, s6, 6
	s_abs_i32 s0, s6
	v_writelane_b32 v250, s0, 7
	s_lshl_b32 s0, s12, 12
	v_writelane_b32 v250, s0, 8
	s_lshl_b32 s0, s12, 10
	v_writelane_b32 v250, s0, 9
	s_add_i32 s0, s12, 0x21e0
	v_writelane_b32 v250, s0, 10
	s_add_i32 s0, 0, 0x20004
	v_writelane_b32 v250, s0, 11
	v_cmp_eq_u32_e64 s[0:1], 0, v0
	v_writelane_b32 v251, s3, 63
	s_mov_b32 s2, 0x800000
	v_writelane_b32 v250, s0, 12
	s_movk_i32 s79, 0x3fff
	s_mov_b32 s80, 0x8002000
	v_writelane_b32 v250, s1, 13
	s_mov_b32 s1, s63
	v_writelane_b32 v250, s0, 14
	s_movk_i32 s81, 0x2000
	s_mov_b32 s82, 0x8004000
	v_writelane_b32 v250, s1, 15
	v_writelane_b32 v250, s67, 16
	v_writelane_b32 v250, s70, 17
	s_mov_b32 s83, 0x8006000
	s_movk_i32 s17, 0x6000
	v_writelane_b32 v250, s71, 18
	v_writelane_b32 v250, s72, 19
	s_mov_b32 s23, 0x8007000
	s_movk_i32 s40, 0x7000
	v_writelane_b32 v250, s73, 20
	v_writelane_b32 v250, s64, 21
	s_movk_i32 s88, 0xc00
	s_movk_i32 s59, 0x1800
	v_writelane_b32 v250, s65, 22
	s_mov_b32 s60, 0x2aaaaaab
	s_mov_b32 s61, 0x3dd53b94
	s_mov_b32 s97, 0xbdcccccd
	s_mov_b32 s96, 0xf800000
	s_mov_b64 s[26:27], 0x60000
	s_mov_b64 s[28:29], 0xc0000
	s_mov_b64 s[30:31], 0x120000
	s_mov_b32 s35, -1
	s_mov_b64 s[36:37], 0x100
	s_mov_b64 s[90:91], 0x40100
	s_mov_b64 s[92:93], 0x80100
	s_mov_b64 s[24:25], 0x40000
	s_mov_b64 s[38:39], 0x80
	v_writelane_b32 v250, s68, 23
	s_nop 1
	v_writelane_b32 v250, s69, 24
	s_branch .LBB0_11

; __global__ void __launch_bounds__(512, 2) fwd_kernel(Params Parg) {
;     ...
;   for (int st2 = 2 * step_lo; st2 < 2 * step_hi; ++st2) {
;     const int st = st2 >> 1;
;     if ((st2 & 1) && !((REPEAT_MASK >> st) & 1)) continue;
.LBB0_10:
	s_add_i32 s66, s66, 1
	s_cmp_ge_i32 s66, s67
	s_cbranch_scc0 .LBB0_11
	s_endpgm

; template <int DK>
; DI void attn_pass(const AttnSrc& s, const int q0, const float sc, LAS unsigned char* lds, f32x16 (&O)[4]) {
;     ...
;   const int NT = (q0 + 256) / 64;
;   const bf16_t* kp[KP]; int kstr[KP]; const bf16_t* vp[2];
; #pragma unroll
;   for (int i = 0; i < KP; ++i) {
;     const int o = (wid + 8 * i) * 1024 + lane * 16, row = o / ROWB, pc = (o % ROWB) >> 4;
;     const int lc = (DK == 64) ? (pc ^ (row & 7)) : ((pc & ~7) | ((pc & 7) ^ ((row >> 1) & 7)));
;     const int e = lc * 8;
;     if (e < s.nk0) { kp[i] = s.k0 + (size_t)row * s.ldk0 + e; kstr[i] = 64 * s.ldk0; } else { kp[i] = s.k1 + (size_t)row * s.ldk1 + (e - s.nk0); kstr[i] = 64 * s.ldk1; }
;   }
; #pragma unroll
;   for (int i = 0; i < 2; ++i) {
;     const int o = (wid + 8 * i) * 1024 + lane * 16, row = o >> 8, pc = (o >> 4) & 15;
;     const int lc = (((pc >> 2) ^ (row & 3)) << 2) | (pc & 3);
;     vp[i] = s.v + (size_t)row * s.ldv + lc * 8;
;   }
;   const int vstr = 64 * s.ldv;
;   const unsigned lds0 = (unsigned)reinterpret_cast<__UINTPTR_TYPE__>(lds);
;   auto issue = [&](int t, int buf) {
; #pragma unroll
;     for (int i = 0; i < KP; ++i) glds16(kp[i] + (size_t)t * kstr[i], (unsigned)__builtin_amdgcn_readfirstlane(lds0 + buf * STG + (wid + 8 * i) * 1024));
; #pragma unroll
;     for (int i = 0; i < 2; ++i) glds16(vp[i] + (size_t)t * vstr, (unsigned)__builtin_amdgcn_readfirstlane(lds0 + buf * STG + KSZ + (wid + 8 * i) * 1024));
;   };
; #pragma unroll
;   for (int i = 0; i < DPF; ++i) issue(i, i);
;   bf16x8 qf[NS];
; #pragma unroll
;   for (int i = 0; i < NS; ++i) qf[i] = *(const bf16x8*)(s.q + (size_t)(qw0 + r) * s.ldq + 16 * i + 8 * h);
; #pragma unroll
;   for (int i = 0; i < NS; ++i) asm volatile("" : "+v"(qf[i]));
.LBB0_99:
	s_xor_b64 s[10:11], s[12:13], -1
	s_lshl_b64 s[14:15], s[14:15], 1
	v_mov_b32_e32 v24, v163
	s_add_u32 s14, s22, s14
	s_addc_u32 s15, s23, s15
	v_readfirstlane_b32 s18, v24
	s_ashr_i32 s18, s18, 6
	s_lshl_b32 s45, s18, 5
	v_and_b32_e32 v0, 63, v24
	s_lshl_b32 s18, s18, 10
	v_lshl_or_b32 v8, v0, 4, s18
	v_ashrrev_i32_e32 v0, 31, v8
	v_lshrrev_b32_e32 v0, 25, v0
	v_add_u32_e32 v0, v8, v0
	v_ashrrev_i32_e32 v3, 7, v0
	v_and_b32_e32 v0, 0xffffff80, v0
	v_sub_u32_e32 v0, v8, v0
	v_ashrrev_i32_e32 v0, 4, v0
	v_lshrrev_b32_e32 v4, 1, v3
	v_bitop3_b32 v9, v0, v4, 7 bitop3:0x78
	v_lshlrev_b32_e32 v2, 3, v9
	v_mov_b64_e32 v[4:5], s[14:15]
	v_mad_i64_i32 v[6:7], s[14:15], v3, s59, v[4:5]
	v_ashrrev_i32_e32 v3, 31, v2
	v_ashrrev_i32_e32 v0, 8, v8
	v_lshl_add_u64 v[2:3], v[2:3], 1, v[6:7]
	v_lshlrev_b32_e32 v6, 2, v0
	v_and_b32_e32 v10, 3, v24
	v_xor_b32_e32 v6, v6, v24
	v_and_or_b32 v11, v6, 12, v10
	v_mul_hi_i32_i24_e32 v7, 0x1800, v0
	v_mul_i32_i24_e32 v6, 0x1800, v0
	v_lshl_add_u64 v[6:7], s[4:5], 0, v[6:7]
	v_lshlrev_b32_e32 v0, 4, v11
	v_lshl_add_u64 v[18:19], v[6:7], 0, v[0:1]
	v_add_u32_e32 v0, 0x2000, v8
	v_ashrrev_i32_e32 v0, 8, v0
	v_lshlrev_b32_e32 v6, 2, v0
	v_xor_b32_e32 v6, v6, v24
	v_and_or_b32 v8, v6, 12, v10
	v_mul_hi_i32_i24_e32 v7, 0x1800, v0
	v_mul_i32_i24_e32 v6, 0x1800, v0
	v_lshl_add_u64 v[6:7], s[4:5], 0, v[6:7]
	v_lshlrev_b32_e32 v0, 4, v8
	v_cmp_gt_i32_e32 vcc, 8, v9
	v_lshl_add_u64 v[20:21], v[6:7], 0, v[0:1]
	s_waitcnt vmcnt(0)
	s_mov_b64 s[14:15], 0x800
	v_cndmask_b32_e64 v7, -1, 0, vcc
	v_cndmask_b32_e64 v6, v200, 0, vcc
	v_lshl_add_u64 v[22:23], v[2:3], 0, v[6:7]
	v_lshl_add_u64 v[2:3], v[22:23], 0, s[14:15]
	s_add_i32 s46, s18, 0
	s_mov_b32 s14, m0
	s_mov_b32 m0, s46
	s_nop 0
	global_load_lds_dwordx4 v[2:3], off
	s_mov_b32 m0, s14
	s_add_i32 s47, s46, 0x2000
	s_mov_b32 s14, m0
	s_mov_b32 m0, s47
	s_nop 0
	global_load_lds_dwordx4 v[18:19], off
	s_mov_b32 m0, s14
	s_add_i32 s52, s46, 0x4000
	s_mov_b32 s14, m0
	s_mov_b32 m0, s52
	s_nop 0
	global_load_lds_dwordx4 v[20:21], off
	s_mov_b32 m0, s14
	s_mov_b64 s[14:15], 0x60800
	v_lshl_add_u64 v[2:3], v[22:23], 0, s[14:15]
	s_add_i32 s14, s46, 0x6000
	s_mov_b32 s15, m0
	s_mov_b32 m0, s14
	s_nop 0
	global_load_lds_dwordx4 v[2:3], off
	s_mov_b32 m0, s15
	v_lshl_add_u64 v[2:3], v[18:19], 0, s[26:27]
	s_add_i32 s14, s46, 0x8000
	s_mov_b32 s15, m0
	s_mov_b32 m0, s14
	s_nop 0
	global_load_lds_dwordx4 v[2:3], off
	s_mov_b32 m0, s15
	v_lshl_add_u64 v[2:3], v[20:21], 0, s[26:27]
	s_add_i32 s14, s46, 0xa000
	s_mov_b32 s15, m0
	s_mov_b32 m0, s14
	s_nop 0
	global_load_lds_dwordx4 v[2:3], off
	s_mov_b32 m0, s15
	s_mov_b64 s[14:15], 0xc0800
	v_lshl_add_u64 v[2:3], v[22:23], 0, s[14:15]
	s_add_i32 s14, s46, 0xc000
	v_and_b32_e32 v25, 31, v24
	s_add_i32 s45, s45, s40
	s_mov_b32 s15, m0
	s_mov_b32 m0, s14
	s_nop 0
	global_load_lds_dwordx4 v[2:3], off
	s_mov_b32 m0, s15
	v_lshl_add_u64 v[2:3], v[18:19], 0, s[28:29]
	s_add_i32 s14, s46, 0xe000
	v_bfe_u32 v26, v24, 5, 1
	s_mov_b32 s15, m0
	s_mov_b32 m0, s14
	s_nop 0
	global_load_lds_dwordx4 v[2:3], off
	s_mov_b32 m0, s15
	v_lshl_add_u64 v[2:3], v[20:21], 0, s[28:29]
	s_add_i32 s14, s46, 0x10000
	v_or_b32_e32 v212, s45, v25
	s_mov_b32 s15, m0
	s_mov_b32 m0, s14
	s_nop 0
	global_load_lds_dwordx4 v[2:3], off
	s_mov_b32 m0, s15
	v_lshlrev_b32_e32 v0, 4, v26
	v_mad_i64_i32 v[2:3], s[14:15], v212, s59, v[4:5]
	v_lshl_add_u64 v[14:15], v[2:3], 0, v[0:1]
	global_load_dwordx4 v[2:5], v[14:15], off
	global_load_dwordx4 v[6:9], v[14:15], off offset:32
	global_load_dwordx4 v[10:13], v[14:15], off offset:64
	s_nop 0
	global_load_dwordx4 v[14:17], v[14:15], off offset:96
	s_mov_b64 s[14:15], 0x120800
	v_lshlrev_b32_e32 v213, 7, v25
	v_lshlrev_b32_e32 v214, 10, v26
	v_lshlrev_b32_e32 v223, 2, v26
	v_lshl_add_u64 v[166:167], v[20:21], 0, s[30:31]
	v_lshl_add_u64 v[168:169], v[18:19], 0, s[30:31]
	v_lshl_add_u64 v[170:171], v[22:23], 0, s[14:15]
	s_mov_b32 s53, 63
	s_mov_b32 s54, 3
	s_mov_b32 s55, 0
	s_or_b32 s56, s45, 31
	v_mov_b32_e32 v227, 0
	s_mov_b32 s57, s44
	s_mov_b64 s[14:15], 0
	s_mov_b32 s58, 3
	s_waitcnt vmcnt(3)
	s_nop 0
	v_lshlrev_b32_e32 v0, 16, v2
	v_and_b32_e32 v2, 0xffff0000, v2
	v_mul_f32_e32 v2, 0x3e38aa3b, v2
	s_waitcnt vmcnt(2)
	s_waitcnt vmcnt(1)
	s_waitcnt vmcnt(0)
; DI unsigned cvt_pk_bf16(float lo, float hi) { unsigned r; asm volatile("v_cvt_pk_bf16_f32 %0, %1, %2" : "=v"(r) : "v"(lo), "v"(hi)); return r; }
; DI float bf_lo(unsigned w) { return __uint_as_float(w << 16); }
; DI float bf_hi(unsigned w) { return __uint_as_float(w & 0xffff0000u); }
; template <int DK>
; DI void attn_pass(const AttnSrc& s, const int q0, const float sc, LAS unsigned char* lds, f32x16 (&O)[4]) {
;     ...
;   if (REL) {
; #pragma unroll
;   for (int i = 0; i < NS; ++i) {
;     const u32x4 w = __builtin_bit_cast(u32x4, qf[i]); u32x4 o;
;     o.x = cvt_pk_bf16(bf_lo(w.x) * sc, bf_hi(w.x) * sc); o.y = cvt_pk_bf16(bf_lo(w.y) * sc, bf_hi(w.y) * sc);
;     o.z = cvt_pk_bf16(bf_lo(w.z) * sc, bf_hi(w.z) * sc); o.w = cvt_pk_bf16(bf_lo(w.w) * sc, bf_hi(w.w) * sc);
;     qf[i] = __builtin_bit_cast(bf16x8, o);
;   }
;   }
;   f32x16 negm;
; #pragma unroll
;   for (int j = 0; j < 16; ++j) negm[j] = 0.f;
;   if (REL) asm volatile("" : "+v"(negm));
;   const int kx = (DK == 64) ? (r & 7) : ((r >> 1) & 7);
;   const int krow = r * ROWB;
;   const int i15 = lane & 15;
;   const int vrow = (4 * h + (i15 >> 2)) * 256 + ((lane >> 4) & 1) * 32 + (lane & 3) * 8;
;   const int vx = (i15 >> 2) & 3;
;   int buf = 0, pbuf = DPF;
;     ...
;     buf = (buf + 1 == NBUF) ? 0 : buf + 1; pbuf = (pbuf + 1 == NBUF) ? 0 : pbuf + 1;
	v_lshlrev_b32_e32 v29, 16, v5
	v_mul_f32_e32 v0, 0x3e38aa3b, v0
	v_cvt_pk_bf16_f32 v128, v0, v2
	v_and_b32_e32 v2, 0xffff0000, v5
	v_lshlrev_b32_e32 v27, 16, v3
	v_and_b32_e32 v3, 0xffff0000, v3
	v_lshlrev_b32_e32 v28, 16, v4
	v_and_b32_e32 v4, 0xffff0000, v4
	v_mul_f32_e32 v0, 0x3e38aa3b, v29
	v_mul_f32_e32 v2, 0x3e38aa3b, v2
	v_mul_f32_e32 v27, 0x3e38aa3b, v27
	v_mul_f32_e32 v3, 0x3e38aa3b, v3
	v_mul_f32_e32 v28, 0x3e38aa3b, v28
	v_mul_f32_e32 v4, 0x3e38aa3b, v4
	v_cvt_pk_bf16_f32 v129, v27, v3
	v_cvt_pk_bf16_f32 v130, v28, v4
	v_cvt_pk_bf16_f32 v131, v0, v2
	v_lshlrev_b32_e32 v0, 16, v6
	v_and_b32_e32 v2, 0xffff0000, v6
	v_mul_f32_e32 v0, 0x3e38aa3b, v0
	v_mul_f32_e32 v2, 0x3e38aa3b, v2
	v_cvt_pk_bf16_f32 v132, v0, v2
	v_lshlrev_b32_e32 v0, 16, v7
	v_and_b32_e32 v2, 0xffff0000, v7
	v_mul_f32_e32 v0, 0x3e38aa3b, v0
	v_mul_f32_e32 v2, 0x3e38aa3b, v2
	v_cvt_pk_bf16_f32 v133, v0, v2
	v_lshlrev_b32_e32 v0, 16, v8
	v_and_b32_e32 v2, 0xffff0000, v8
	v_mul_f32_e32 v0, 0x3e38aa3b, v0
	v_mul_f32_e32 v2, 0x3e38aa3b, v2
	v_cvt_pk_bf16_f32 v134, v0, v2
	v_lshlrev_b32_e32 v0, 16, v9
	v_and_b32_e32 v2, 0xffff0000, v9
	v_mul_f32_e32 v0, 0x3e38aa3b, v0
	v_mul_f32_e32 v2, 0x3e38aa3b, v2
	v_cvt_pk_bf16_f32 v135, v0, v2
	v_lshlrev_b32_e32 v0, 16, v10
	v_and_b32_e32 v2, 0xffff0000, v10
	v_mul_f32_e32 v0, 0x3e38aa3b, v0
	v_mul_f32_e32 v2, 0x3e38aa3b, v2
	v_cvt_pk_bf16_f32 v136, v0, v2
	v_lshlrev_b32_e32 v0, 16, v11
	v_and_b32_e32 v2, 0xffff0000, v11
	v_mul_f32_e32 v0, 0x3e38aa3b, v0
	v_mul_f32_e32 v2, 0x3e38aa3b, v2
	v_cvt_pk_bf16_f32 v137, v0, v2
	v_lshlrev_b32_e32 v0, 16, v12
	v_and_b32_e32 v2, 0xffff0000, v12
	v_mul_f32_e32 v0, 0x3e38aa3b, v0
	v_mul_f32_e32 v2, 0x3e38aa3b, v2
	v_cvt_pk_bf16_f32 v138, v0, v2
	v_lshlrev_b32_e32 v0, 16, v13
	v_and_b32_e32 v2, 0xffff0000, v13
	v_mul_f32_e32 v0, 0x3e38aa3b, v0
	v_mul_f32_e32 v2, 0x3e38aa3b, v2
	v_cvt_pk_bf16_f32 v139, v0, v2
	v_lshlrev_b32_e32 v0, 16, v14
	v_and_b32_e32 v2, 0xffff0000, v14
	v_mul_f32_e32 v0, 0x3e38aa3b, v0
	v_mul_f32_e32 v2, 0x3e38aa3b, v2
	v_cvt_pk_bf16_f32 v140, v0, v2
	v_lshlrev_b32_e32 v0, 16, v15
	v_and_b32_e32 v2, 0xffff0000, v15
	v_mul_f32_e32 v0, 0x3e38aa3b, v0
	v_mul_f32_e32 v2, 0x3e38aa3b, v2
	v_cvt_pk_bf16_f32 v141, v0, v2
	v_lshlrev_b32_e32 v0, 16, v16
	v_and_b32_e32 v2, 0xffff0000, v16
	v_mul_f32_e32 v0, 0x3e38aa3b, v0
	v_mul_f32_e32 v2, 0x3e38aa3b, v2
	v_cvt_pk_bf16_f32 v142, v0, v2
	v_lshlrev_b32_e32 v0, 16, v17
	v_and_b32_e32 v2, 0xffff0000, v17
	v_lshlrev_b32_e32 v17, 1, v24
	v_and_b32_e32 v216, 32, v17
	v_lshlrev_b32_e32 v17, 3, v24
	v_bfe_u32 v16, v24, 2, 2
	v_and_b32_e32 v217, 24, v17
	v_bfe_u32 v17, v24, 1, 3
	v_bitop3_b32 v24, v26, v17, 7 bitop3:0x78
	v_lshlrev_b32_e32 v218, 4, v24
	v_bitop3_b32 v24, v26, v17, 2 bitop3:0x36
	v_mul_f32_e32 v0, 0x3e38aa3b, v0
	v_mul_f32_e32 v2, 0x3e38aa3b, v2
	v_mov_b32_e32 v14, v1
	v_mov_b32_e32 v15, v1
	v_lshlrev_b32_e32 v219, 4, v24
	v_bitop3_b32 v24, v26, v17, 4 bitop3:0x36
	v_bitop3_b32 v17, v26, v17, 6 bitop3:0x36
	v_cvt_pk_bf16_f32 v143, v0, v2
	v_mov_b32_e32 v0, v1
	v_mov_b32_e32 v2, v1
	v_mov_b32_e32 v3, v1
	v_mov_b32_e32 v4, v1
	v_mov_b32_e32 v5, v1
	v_mov_b32_e32 v6, v1
	v_mov_b32_e32 v7, v1
	v_mov_b32_e32 v8, v1
	v_mov_b32_e32 v9, v1
	v_mov_b32_e32 v10, v1
	v_mov_b32_e32 v11, v1
	v_mov_b32_e32 v12, v1
	v_mov_b32_e32 v13, v1
	v_mov_b64_e32 v[94:95], v[14:15]
	v_lshlrev_b32_e32 v215, 8, v16
	v_lshlrev_b32_e32 v220, 4, v24
	v_lshlrev_b32_e32 v221, 4, v17
	v_lshlrev_b32_e32 v222, 6, v16
	v_mov_b64_e32 v[30:31], v[14:15]
	v_mov_b64_e32 v[46:47], v[14:15]
	v_mov_b64_e32 v[62:63], v[14:15]
	v_mov_b64_e32 v[78:79], v[14:15]
	v_mov_b64_e32 v[92:93], v[12:13]
	v_mov_b64_e32 v[90:91], v[10:11]
	v_mov_b64_e32 v[88:89], v[8:9]
	v_mov_b64_e32 v[86:87], v[6:7]
	v_mov_b64_e32 v[84:85], v[4:5]
	v_mov_b64_e32 v[82:83], v[2:3]
	v_mov_b64_e32 v[80:81], v[0:1]
	v_xor_b32_e32 v224, 64, v222
	v_xor_b32_e32 v225, 0x80, v222
	v_xor_b32_e32 v226, 0xc0, v222
	v_mov_b64_e32 v[28:29], v[12:13]
	v_mov_b64_e32 v[26:27], v[10:11]
	v_mov_b64_e32 v[24:25], v[8:9]
	v_mov_b64_e32 v[22:23], v[6:7]
	v_mov_b64_e32 v[20:21], v[4:5]
	v_mov_b64_e32 v[18:19], v[2:3]
	v_mov_b64_e32 v[16:17], v[0:1]
	v_mov_b64_e32 v[44:45], v[12:13]
	v_mov_b64_e32 v[42:43], v[10:11]
	v_mov_b64_e32 v[40:41], v[8:9]
	v_mov_b64_e32 v[38:39], v[6:7]
	v_mov_b64_e32 v[36:37], v[4:5]
	v_mov_b64_e32 v[34:35], v[2:3]
	v_mov_b64_e32 v[32:33], v[0:1]
	v_mov_b64_e32 v[60:61], v[12:13]
	v_mov_b64_e32 v[58:59], v[10:11]
	v_mov_b64_e32 v[56:57], v[8:9]
	v_mov_b64_e32 v[54:55], v[6:7]
	v_mov_b64_e32 v[52:53], v[4:5]
	v_mov_b64_e32 v[50:51], v[2:3]
	v_mov_b64_e32 v[48:49], v[0:1]
	v_mov_b64_e32 v[76:77], v[12:13]
	v_mov_b64_e32 v[74:75], v[10:11]
	v_mov_b64_e32 v[72:73], v[8:9]
	v_mov_b64_e32 v[70:71], v[6:7]
	v_mov_b64_e32 v[68:69], v[4:5]
	v_mov_b64_e32 v[66:67], v[2:3]
	v_mov_b64_e32 v[64:65], v[0:1]
	v_mov_b32_e32 v14, 0
	s_sub_i32 s18, s45, s40
	s_cmp_ge_u32 s18, 0x80
	s_cbranch_scc1 .Lb64_loop
	s_branch .LBB0_102
.LBB0_101:
	s_add_i32 s18, s55, 1
	s_cmp_lg_u32 s18, 5
	s_cselect_b32 s55, s18, 0
	s_add_i32 s18, s58, 1
	s_cmp_lg_u32 s18, 5
	s_cselect_b32 s58, s18, 0
	s_add_u32 s14, s14, 0x60000
	s_addc_u32 s15, s15, 0
	s_add_i32 s53, s53, 64
	s_add_i32 s54, s54, 1
	s_add_i32 s57, s57, -1
	s_cmp_lg_u32 s42, s14
	s_cbranch_scc0 .LBB0_117

; #define LAS __attribute__((address_space(3)))
; template <int DK>
; DI void attn_pass(const AttnSrc& s, const int q0, const float sc, LAS unsigned char* lds, f32x16 (&O)[4]) {
;     ...
;     if (t + DPF < NT) issue(t + DPF, pbuf);
;     if (64 * t <= qw0 + 31) {
;       LAS unsigned char* Kb = lds + buf * STG; LAS unsigned char* Vb = lds + buf * STG + KSZ;
;       f32x16 p0, p1;
;       constexpr int GS = (DK == 64) ? 4 : 2, NG = NS / GS;
;       bf16x8 kfa[2][GS], kfb[2][GS];
;       auto kload = [&](int g, int slot) {
; #pragma unroll
;         for (int j = 0; j < GS; ++j) { const int lc = 2 * (g * GS + j) + h; const int ph = (DK == 64) ? (lc ^ kx) : ((lc & ~7) | ((lc & 7) ^ kx));
;           kfa[slot][j] = *(const LAS bf16x8*)(Kb + krow + ph * 16); kfb[slot][j] = *(const LAS bf16x8*)(Kb + krow + 32 * ROWB + ph * 16); }
;       };
;       kload(0, 0);
; #pragma unroll
;       for (int g = 0; g < NG; ++g) {
;         if (g + 1 < NG) kload(g + 1, (g + 1) & 1);
;         __builtin_amdgcn_s_setprio(1);
; #pragma unroll
;         for (int j = 0; j < GS; ++j) {
;           if (g == 0 && j == 0) {
;             if (REL) {
;               p0 = __builtin_amdgcn_mfma_f32_32x32x16_bf16(kfa[0][0], qf[0], negm, 0, 0, 0);
;               p1 = __builtin_amdgcn_mfma_f32_32x32x16_bf16(kfb[0][0], qf[0], negm, 0, 0, 0);
;             } else {
;               f32x16 z;
; #pragma unroll
;               for (int jj = 0; jj < 16; ++jj) z[jj] = 0.f;
;               p0 = __builtin_amdgcn_mfma_f32_32x32x16_bf16(kfa[0][0], qf[0], z, 0, 0, 0);
;               p1 = __builtin_amdgcn_mfma_f32_32x32x16_bf16(kfb[0][0], qf[0], z, 0, 0, 0);
;             }
;           } else {
;             p0 = __builtin_amdgcn_mfma_f32_32x32x16_bf16(kfa[g & 1][j], qf[g * GS + j], p0, 0, 0, 0);
;             p1 = __builtin_amdgcn_mfma_f32_32x32x16_bf16(kfb[g & 1][j], qf[g * GS + j], p1, 0, 0, 0);
;           }
;         }
;         __builtin_amdgcn_s_setprio(0);
;       }
.LBB0_112:
	s_sub_i32 s18, s53, 63
	s_cmp_gt_i32 s18, s56
	s_cbranch_scc0 .La64_act
	s_cmp_ge_u32 s54, s41
	s_cbranch_scc1 .LBB0_101
	s_mul_i32 s18, s58, 0x6000
	v_lshl_add_u64 v[2:3], v[170:171], 0, s[14:15]
	s_add_i32 s19, s18, s46
	s_mov_b32 s62, m0
	s_mov_b32 m0, s19
	s_nop 0
	global_load_lds_dwordx4 v[2:3], off
	s_mov_b32 m0, s62
	v_lshl_add_u64 v[2:3], v[168:169], 0, s[14:15]
	s_add_i32 s19, s18, s47
	s_mov_b32 s62, m0
	s_mov_b32 m0, s19
	s_nop 0
	global_load_lds_dwordx4 v[2:3], off
	s_mov_b32 m0, s62
	v_lshl_add_u64 v[2:3], v[166:167], 0, s[14:15]
	s_add_i32 s18, s18, s52
	s_mov_b32 s19, m0
	s_mov_b32 m0, s18
	s_nop 0
	global_load_lds_dwordx4 v[2:3], off
	s_mov_b32 m0, s19
	s_branch .LBB0_101
.La64_act:
	s_mul_i32 s18, s55, 0x6000
	s_add_i32 s18, s18, 0
	v_add_u32_e32 v0, s18, v213
	v_add_u32_e32 v6, v0, v218
	v_add_u32_e32 v15, v0, v219
	ds_read_b128 v[2:5], v6
	ds_read_b128 v[6:9], v6 offset:4096
	ds_read_b128 v[10:13], v15
	ds_read_b128 v[144:147], v15 offset:4096
	v_add_u32_e32 v15, v0, v220
	v_add_u32_e32 v0, v0, v221
	ds_read_b128 v[230:233], v15
	ds_read_b128 v[234:237], v15 offset:4096
	ds_read_b128 v[238:241], v0
	ds_read_b128 v[242:245], v0 offset:4096
	s_setprio 1
	s_waitcnt lgkmcnt(6)
	v_mfma_f32_32x32x16_bf16 v[112:127], v[2:5], v[128:131], v[80:95]
	v_mfma_f32_32x32x16_bf16 v[96:111], v[6:9], v[128:131], v[80:95]
	s_waitcnt lgkmcnt(4)
	v_mfma_f32_32x32x16_bf16 v[112:127], v[10:13], v[132:135], v[112:127]
	v_mfma_f32_32x32x16_bf16 v[96:111], v[144:147], v[132:135], v[96:111]
	s_waitcnt lgkmcnt(2)
	v_mfma_f32_32x32x16_bf16 v[112:127], v[230:233], v[136:139], v[112:127]
	v_mfma_f32_32x32x16_bf16 v[96:111], v[234:237], v[136:139], v[96:111]
	s_waitcnt lgkmcnt(0)
	v_mfma_f32_32x32x16_bf16 v[112:127], v[238:241], v[140:143], v[112:127]
	v_mfma_f32_32x32x16_bf16 v[96:111], v[242:245], v[140:143], v[96:111]
	s_setprio 0
	v_add3_u32 v0, s18, v214, v215
	v_add3_u32 v15, v0, v216, v217
	v_add_u32_e32 v246, v15, v222
	v_add_u32_e32 v247, v15, v224
	v_add_u32_e32 v248, v15, v225
	v_add_u32_e32 v249, v15, v226
	s_cmp_ge_u32 s54, s41
	s_cbranch_scc1 .La64_dmadone
	s_mul_i32 s18, s58, 0x6000
	v_lshl_add_u64 v[2:3], v[170:171], 0, s[14:15]
	s_add_i32 s19, s18, s46
	s_mov_b32 s62, m0
	s_mov_b32 m0, s19
	s_nop 0
	global_load_lds_dwordx4 v[2:3], off
	s_mov_b32 m0, s62
	v_lshl_add_u64 v[2:3], v[168:169], 0, s[14:15]
	s_add_i32 s19, s18, s47
	s_mov_b32 s62, m0
	s_mov_b32 m0, s19
	s_nop 0
	global_load_lds_dwordx4 v[2:3], off
	s_mov_b32 m0, s62
	v_lshl_add_u64 v[2:3], v[166:167], 0, s[14:15]
	s_add_i32 s18, s18, s52
	s_mov_b32 s19, m0
	s_mov_b32 m0, s18
	s_nop 0
	global_load_lds_dwordx4 v[2:3], off
	s_mov_b32 m0, s19

; template <int DK>
; DI void attn_pass(const AttnSrc& s, const int q0, const float sc, LAS unsigned char* lds, f32x16 (&O)[4]) {
;     ...
;     { const int rem = NT - 1 - t;
;       if (rem >= DPF - 1) asm volatile("s_waitcnt vmcnt(%0)" :: "n"((DPF - 1) * PT) : "memory");
;       else if (rem == 1) asm volatile("s_waitcnt vmcnt(%0)" :: "n"(PT) : "memory");
;       else asm volatile("s_waitcnt vmcnt(0)" ::: "memory"); }
;     ...
; #pragma unroll
;         for (int j = 0; j < 16; ++j) { p0[j] = __builtin_amdgcn_exp2f(p0[j]); p1[j] = __builtin_amdgcn_exp2f(p1[j]); rs += p0[j] + p1[j]; }
;       } else {
;         const float cand = mx * sc;
;         const bool grow = cand > mrun + 8.f;
;         if (__builtin_amdgcn_ballot_w64(grow) != 0ull) {
;           const float mnew = grow ? cand : mrun;
;           const float alpha = __builtin_amdgcn_exp2f(mrun - mnew);
;           mrun = mnew; lrun *= alpha;
; #pragma unroll
;           for (int i = 0; i < 4; ++i)
; #pragma unroll
;             for (int j = 0; j < 16; ++j) O[i][j] *= alpha;
;         }
; #pragma unroll
;         for (int j = 0; j < 16; ++j) { p0[j] = __builtin_amdgcn_exp2f(p0[j] * sc - mrun); p1[j] = __builtin_amdgcn_exp2f(p1[j] * sc - mrun); rs += p0[j] + p1[j]; }
;       }
;       lrun += rs;
;       bf16x8 pb[4];
;       { u32x4 w;
;         w.x = cvt_pk_bf16(p0[0], p0[1]); w.y = cvt_pk_bf16(p0[2], p0[3]); w.z = cvt_pk_bf16(p0[4], p0[5]); w.w = cvt_pk_bf16(p0[6], p0[7]); pb[0] = __builtin_bit_cast(bf16x8, w);
;         w.x = cvt_pk_bf16(p0[8], p0[9]); w.y = cvt_pk_bf16(p0[10], p0[11]); w.z = cvt_pk_bf16(p0[12], p0[13]); w.w = cvt_pk_bf16(p0[14], p0[15]); pb[1] = __builtin_bit_cast(bf16x8, w);
;         w.x = cvt_pk_bf16(p1[0], p1[1]); w.y = cvt_pk_bf16(p1[2], p1[3]); w.z = cvt_pk_bf16(p1[4], p1[5]); w.w = cvt_pk_bf16(p1[6], p1[7]); pb[2] = __builtin_bit_cast(bf16x8, w);
;         w.x = cvt_pk_bf16(p1[8], p1[9]); w.y = cvt_pk_bf16(p1[10], p1[11]); w.z = cvt_pk_bf16(p1[12], p1[13]); w.w = cvt_pk_bf16(p1[14], p1[15]); pb[3] = __builtin_bit_cast(bf16x8, w); }
; #pragma unroll
;       for (int vt = 0; vt < 4; ++vt) {
;         if (vt + 1 < 4) vload(vt + 1, (vt + 1) & 1);
;         __builtin_amdgcn_s_setprio(1);
; #pragma unroll
;         for (int ks = 0; ks < 4; ++ks) O[vt] = __builtin_amdgcn_mfma_f32_32x32x16_bf16(vf[vt & 1][ks], pb[ks], O[vt], 0, 0, 0);
;         __builtin_amdgcn_s_setprio(0);
;       }
.La64_exp:
	v_exp_f32_e32 v112, v112
	v_exp_f32_e32 v113, v113
	v_exp_f32_e32 v114, v114
	v_exp_f32_e32 v115, v115
	v_exp_f32_e32 v116, v116
	v_exp_f32_e32 v117, v117
	v_exp_f32_e32 v118, v118
	v_exp_f32_e32 v119, v119
	v_add_f32_e32 v0, v112, v113
	v_add_f32_e32 v15, v114, v115
	v_add_f32_e32 v0, v0, v116
	v_add_f32_e32 v15, v15, v117
	v_add_f32_e32 v0, v0, v118
	v_add_f32_e32 v15, v15, v119
	v_cvt_pk_bf16_f32 v112, v112, v113
	v_cvt_pk_bf16_f32 v113, v114, v115
	v_cvt_pk_bf16_f32 v114, v116, v117
	v_cvt_pk_bf16_f32 v115, v118, v119
	ds_read_b64_tr_b16 v[230:231], v246 offset:12288
	ds_read_b64_tr_b16 v[232:233], v246 offset:14336
	ds_read_b64_tr_b16 v[234:235], v247 offset:12288
	ds_read_b64_tr_b16 v[236:237], v247 offset:14336
	ds_read_b64_tr_b16 v[238:239], v248 offset:12288
	ds_read_b64_tr_b16 v[240:241], v248 offset:14336
	ds_read_b64_tr_b16 v[242:243], v249 offset:12288
	ds_read_b64_tr_b16 v[244:245], v249 offset:14336
	s_setprio 1
	s_waitcnt lgkmcnt(14)
	v_mfma_f32_32x32x16_bf16 v[64:79], v[2:5], v[112:115], v[64:79]
	s_waitcnt lgkmcnt(12)
	v_mfma_f32_32x32x16_bf16 v[48:63], v[6:9], v[112:115], v[48:63]
	s_waitcnt lgkmcnt(10)
	v_mfma_f32_32x32x16_bf16 v[32:47], v[10:13], v[112:115], v[32:47]
	s_waitcnt lgkmcnt(8)
	v_mfma_f32_32x32x16_bf16 v[16:31], v[144:147], v[112:115], v[16:31]
	v_exp_f32_e32 v120, v120
	v_exp_f32_e32 v121, v121
	v_exp_f32_e32 v122, v122
	v_exp_f32_e32 v123, v123
	v_exp_f32_e32 v124, v124
	v_exp_f32_e32 v125, v125
	v_exp_f32_e32 v126, v126
	v_exp_f32_e32 v127, v127
	v_add_f32_e32 v0, v0, v120
	v_add_f32_e32 v15, v15, v121
	v_add_f32_e32 v0, v0, v122
	v_add_f32_e32 v15, v15, v123
	v_add_f32_e32 v0, v0, v124
	v_add_f32_e32 v15, v15, v125
	v_add_f32_e32 v0, v0, v126
	v_add_f32_e32 v15, v15, v127
	v_cvt_pk_bf16_f32 v116, v120, v121
	v_cvt_pk_bf16_f32 v117, v122, v123
	v_cvt_pk_bf16_f32 v118, v124, v125
	v_cvt_pk_bf16_f32 v119, v126, v127
	ds_read_b64_tr_b16 v[2:3], v246 offset:16384
	ds_read_b64_tr_b16 v[4:5], v246 offset:18432
	ds_read_b64_tr_b16 v[6:7], v247 offset:16384
	ds_read_b64_tr_b16 v[8:9], v247 offset:18432
	ds_read_b64_tr_b16 v[10:11], v248 offset:16384
	ds_read_b64_tr_b16 v[12:13], v248 offset:18432
	ds_read_b64_tr_b16 v[144:145], v249 offset:16384
	ds_read_b64_tr_b16 v[146:147], v249 offset:18432
	s_waitcnt lgkmcnt(14)
	v_mfma_f32_32x32x16_bf16 v[64:79], v[230:233], v[116:119], v[64:79]
	s_waitcnt lgkmcnt(12)
	v_mfma_f32_32x32x16_bf16 v[48:63], v[234:237], v[116:119], v[48:63]
	s_waitcnt lgkmcnt(10)
	v_mfma_f32_32x32x16_bf16 v[32:47], v[238:241], v[116:119], v[32:47]
	s_waitcnt lgkmcnt(8)
	v_mfma_f32_32x32x16_bf16 v[16:31], v[242:245], v[116:119], v[16:31]
	v_exp_f32_e32 v96, v96
	v_exp_f32_e32 v97, v97
	v_exp_f32_e32 v98, v98
	v_exp_f32_e32 v99, v99
	v_exp_f32_e32 v100, v100
	v_exp_f32_e32 v101, v101
	v_exp_f32_e32 v102, v102
	v_exp_f32_e32 v103, v103
	v_add_f32_e32 v0, v0, v96
	v_add_f32_e32 v15, v15, v97
	v_add_f32_e32 v0, v0, v98
	v_add_f32_e32 v15, v15, v99
	v_add_f32_e32 v0, v0, v100
	v_add_f32_e32 v15, v15, v101
	v_add_f32_e32 v0, v0, v102
	v_add_f32_e32 v15, v15, v103
	v_cvt_pk_bf16_f32 v96, v96, v97
	v_cvt_pk_bf16_f32 v97, v98, v99
	v_cvt_pk_bf16_f32 v98, v100, v101
	v_cvt_pk_bf16_f32 v99, v102, v103
	ds_read_b64_tr_b16 v[230:231], v246 offset:20480
	ds_read_b64_tr_b16 v[232:233], v246 offset:22528
	ds_read_b64_tr_b16 v[234:235], v247 offset:20480
	ds_read_b64_tr_b16 v[236:237], v247 offset:22528
	ds_read_b64_tr_b16 v[238:239], v248 offset:20480
	ds_read_b64_tr_b16 v[240:241], v248 offset:22528
	ds_read_b64_tr_b16 v[242:243], v249 offset:20480
	ds_read_b64_tr_b16 v[244:245], v249 offset:22528
	s_waitcnt lgkmcnt(14)
	v_mfma_f32_32x32x16_bf16 v[64:79], v[2:5], v[96:99], v[64:79]
	s_waitcnt lgkmcnt(12)
	v_mfma_f32_32x32x16_bf16 v[48:63], v[6:9], v[96:99], v[48:63]
	s_waitcnt lgkmcnt(10)
	v_mfma_f32_32x32x16_bf16 v[32:47], v[10:13], v[96:99], v[32:47]
	s_waitcnt lgkmcnt(8)
	v_mfma_f32_32x32x16_bf16 v[16:31], v[144:147], v[96:99], v[16:31]
	v_exp_f32_e32 v104, v104
	v_exp_f32_e32 v105, v105
	v_exp_f32_e32 v106, v106
	v_exp_f32_e32 v107, v107
	v_exp_f32_e32 v108, v108
	v_exp_f32_e32 v109, v109
	v_exp_f32_e32 v110, v110
	v_exp_f32_e32 v111, v111
	v_add_f32_e32 v0, v0, v104
	v_add_f32_e32 v15, v15, v105
	v_add_f32_e32 v0, v0, v106
	v_add_f32_e32 v15, v15, v107
	v_add_f32_e32 v0, v0, v108
	v_add_f32_e32 v15, v15, v109
	v_add_f32_e32 v0, v0, v110
	v_add_f32_e32 v15, v15, v111
	v_cvt_pk_bf16_f32 v100, v104, v105
	v_cvt_pk_bf16_f32 v101, v106, v107
	v_cvt_pk_bf16_f32 v102, v108, v109
	v_cvt_pk_bf16_f32 v103, v110, v111
	s_nop 1
	s_waitcnt lgkmcnt(6)
	v_mfma_f32_32x32x16_bf16 v[64:79], v[230:233], v[100:103], v[64:79]
	s_waitcnt lgkmcnt(4)
	v_mfma_f32_32x32x16_bf16 v[48:63], v[234:237], v[100:103], v[48:63]
	s_waitcnt lgkmcnt(2)
	v_mfma_f32_32x32x16_bf16 v[32:47], v[238:241], v[100:103], v[32:47]
	s_waitcnt lgkmcnt(0)
	v_mfma_f32_32x32x16_bf16 v[16:31], v[242:245], v[100:103], v[16:31]
	s_setprio 0
	v_add_f32_e32 v0, v0, v15
	v_add_f32_e32 v14, v14, v0
	s_branch .LBB0_101
.Lb64_loop:
	s_cmp_lt_i32 s57, 2
	s_mov_b64 s[18:19], -1
	s_cbranch_scc0 .Lb64_w8
	s_cmp_lg_u32 s43, s14
	s_cbranch_scc0 .Lb64_w5
	s_waitcnt vmcnt(0)
	s_mov_b64 s[18:19], 0

; DI unsigned cvt_pk_bf16(float lo, float hi) { unsigned r; asm volatile("v_cvt_pk_bf16_f32 %0, %1, %2" : "=v"(r) : "v"(lo), "v"(hi)); return r; }
; template <int DK>
; DI void attn_pass(const AttnSrc& s, const int q0, const float sc, LAS unsigned char* lds, f32x16 (&O)[4]) {
;     ...
; #pragma unroll
;         for (int j = 0; j < 16; ++j) { p0[j] = __builtin_amdgcn_exp2f(p0[j]); p1[j] = __builtin_amdgcn_exp2f(p1[j]); rs += p0[j] + p1[j]; }
;       } else {
;         const float cand = mx * sc;
;         const bool grow = cand > mrun + 8.f;
;         if (__builtin_amdgcn_ballot_w64(grow) != 0ull) {
;           const float mnew = grow ? cand : mrun;
;           const float alpha = __builtin_amdgcn_exp2f(mrun - mnew);
;           mrun = mnew; lrun *= alpha;
; #pragma unroll
;           for (int i = 0; i < 4; ++i)
; #pragma unroll
;             for (int j = 0; j < 16; ++j) O[i][j] *= alpha;
;         }
; #pragma unroll
;         for (int j = 0; j < 16; ++j) { p0[j] = __builtin_amdgcn_exp2f(p0[j] * sc - mrun); p1[j] = __builtin_amdgcn_exp2f(p1[j] * sc - mrun); rs += p0[j] + p1[j]; }
;       }
;       lrun += rs;
;       bf16x8 pb[4];
;       { u32x4 w;
;         w.x = cvt_pk_bf16(p0[0], p0[1]); w.y = cvt_pk_bf16(p0[2], p0[3]); w.z = cvt_pk_bf16(p0[4], p0[5]); w.w = cvt_pk_bf16(p0[6], p0[7]); pb[0] = __builtin_bit_cast(bf16x8, w);
;         w.x = cvt_pk_bf16(p0[8], p0[9]); w.y = cvt_pk_bf16(p0[10], p0[11]); w.z = cvt_pk_bf16(p0[12], p0[13]); w.w = cvt_pk_bf16(p0[14], p0[15]); pb[1] = __builtin_bit_cast(bf16x8, w);
;         w.x = cvt_pk_bf16(p1[0], p1[1]); w.y = cvt_pk_bf16(p1[2], p1[3]); w.z = cvt_pk_bf16(p1[4], p1[5]); w.w = cvt_pk_bf16(p1[6], p1[7]); pb[2] = __builtin_bit_cast(bf16x8, w);
;         w.x = cvt_pk_bf16(p1[8], p1[9]); w.y = cvt_pk_bf16(p1[10], p1[11]); w.z = cvt_pk_bf16(p1[12], p1[13]); w.w = cvt_pk_bf16(p1[14], p1[15]); pb[3] = __builtin_bit_cast(bf16x8, w); }
; #pragma unroll
;       for (int vt = 0; vt < 4; ++vt) {
;         if (vt + 1 < 4) vload(vt + 1, (vt + 1) & 1);
;         __builtin_amdgcn_s_setprio(1);
; #pragma unroll
;         for (int ks = 0; ks < 4; ++ks) O[vt] = __builtin_amdgcn_mfma_f32_32x32x16_bf16(vf[vt & 1][ks], pb[ks], O[vt], 0, 0, 0);
;         __builtin_amdgcn_s_setprio(0);
;       }
.Lb64_w10:
	s_barrier
	s_cmp_eq_u32 s53, 63
	s_cbranch_scc1 .Lb64_nopv
	s_sub_i32 s18, s53, 0x7f
	s_cmp_gt_i32 s18, s56
	s_cbranch_scc1 .Lb64_nopv
	ds_read_b64_tr_b16 v[230:231], v246 offset:12288
	ds_read_b64_tr_b16 v[232:233], v246 offset:14336
	ds_read_b64_tr_b16 v[234:235], v247 offset:12288
	ds_read_b64_tr_b16 v[236:237], v247 offset:14336
	ds_read_b64_tr_b16 v[238:239], v248 offset:12288
	ds_read_b64_tr_b16 v[240:241], v248 offset:14336
	ds_read_b64_tr_b16 v[242:243], v249 offset:12288
	ds_read_b64_tr_b16 v[244:245], v249 offset:14336
	s_setprio 1
	s_waitcnt lgkmcnt(14)
	v_mfma_f32_32x32x16_bf16 v[64:79], v[2:5], v[112:115], v[64:79]
	s_waitcnt lgkmcnt(12)
	v_mfma_f32_32x32x16_bf16 v[48:63], v[6:9], v[112:115], v[48:63]
	s_waitcnt lgkmcnt(10)
	v_mfma_f32_32x32x16_bf16 v[32:47], v[10:13], v[112:115], v[32:47]
	s_waitcnt lgkmcnt(8)
	v_mfma_f32_32x32x16_bf16 v[16:31], v[144:147], v[112:115], v[16:31]
	v_exp_f32_e32 v120, v120
	v_exp_f32_e32 v121, v121
	v_exp_f32_e32 v122, v122
	v_exp_f32_e32 v123, v123
	v_exp_f32_e32 v124, v124
	v_exp_f32_e32 v125, v125
	v_exp_f32_e32 v126, v126
	v_exp_f32_e32 v127, v127
	v_add_f32_e32 v0, v0, v120
	v_add_f32_e32 v15, v15, v121
	v_add_f32_e32 v0, v0, v122
	v_add_f32_e32 v15, v15, v123
	v_add_f32_e32 v0, v0, v124
	v_add_f32_e32 v15, v15, v125
	v_add_f32_e32 v0, v0, v126
	v_add_f32_e32 v15, v15, v127
	v_cvt_pk_bf16_f32 v116, v120, v121
	v_cvt_pk_bf16_f32 v117, v122, v123
	v_cvt_pk_bf16_f32 v118, v124, v125
	v_cvt_pk_bf16_f32 v119, v126, v127
	ds_read_b64_tr_b16 v[2:3], v246 offset:16384
	ds_read_b64_tr_b16 v[4:5], v246 offset:18432
	ds_read_b64_tr_b16 v[6:7], v247 offset:16384
	ds_read_b64_tr_b16 v[8:9], v247 offset:18432
	ds_read_b64_tr_b16 v[10:11], v248 offset:16384
	ds_read_b64_tr_b16 v[12:13], v248 offset:18432
	ds_read_b64_tr_b16 v[144:145], v249 offset:16384
	ds_read_b64_tr_b16 v[146:147], v249 offset:18432
	s_waitcnt lgkmcnt(14)
	v_mfma_f32_32x32x16_bf16 v[64:79], v[230:233], v[116:119], v[64:79]
	s_waitcnt lgkmcnt(12)
	v_mfma_f32_32x32x16_bf16 v[48:63], v[234:237], v[116:119], v[48:63]
	s_waitcnt lgkmcnt(10)
	v_mfma_f32_32x32x16_bf16 v[32:47], v[238:241], v[116:119], v[32:47]
	s_waitcnt lgkmcnt(8)
	v_mfma_f32_32x32x16_bf16 v[16:31], v[242:245], v[116:119], v[16:31]
	v_exp_f32_e32 v96, v96
	v_exp_f32_e32 v97, v97
	v_exp_f32_e32 v98, v98
	v_exp_f32_e32 v99, v99
	v_exp_f32_e32 v100, v100
	v_exp_f32_e32 v101, v101
	v_exp_f32_e32 v102, v102
	v_exp_f32_e32 v103, v103
	v_add_f32_e32 v0, v0, v96
	v_add_f32_e32 v15, v15, v97
	v_add_f32_e32 v0, v0, v98
	v_add_f32_e32 v15, v15, v99
	v_add_f32_e32 v0, v0, v100
	v_add_f32_e32 v15, v15, v101
	v_add_f32_e32 v0, v0, v102
	v_add_f32_e32 v15, v15, v103
	v_cvt_pk_bf16_f32 v96, v96, v97
	v_cvt_pk_bf16_f32 v97, v98, v99
	v_cvt_pk_bf16_f32 v98, v100, v101
	v_cvt_pk_bf16_f32 v99, v102, v103
	ds_read_b64_tr_b16 v[230:231], v246 offset:20480
	ds_read_b64_tr_b16 v[232:233], v246 offset:22528
	ds_read_b64_tr_b16 v[234:235], v247 offset:20480
	ds_read_b64_tr_b16 v[236:237], v247 offset:22528
	ds_read_b64_tr_b16 v[238:239], v248 offset:20480
	ds_read_b64_tr_b16 v[240:241], v248 offset:22528
	ds_read_b64_tr_b16 v[242:243], v249 offset:20480
	ds_read_b64_tr_b16 v[244:245], v249 offset:22528
	s_waitcnt lgkmcnt(14)
	v_mfma_f32_32x32x16_bf16 v[64:79], v[2:5], v[96:99], v[64:79]
	s_waitcnt lgkmcnt(12)
	v_mfma_f32_32x32x16_bf16 v[48:63], v[6:9], v[96:99], v[48:63]
	s_waitcnt lgkmcnt(10)
	v_mfma_f32_32x32x16_bf16 v[32:47], v[10:13], v[96:99], v[32:47]
	s_waitcnt lgkmcnt(8)
	v_mfma_f32_32x32x16_bf16 v[16:31], v[144:147], v[96:99], v[16:31]
	v_exp_f32_e32 v104, v104
	v_exp_f32_e32 v105, v105
	v_exp_f32_e32 v106, v106
	v_exp_f32_e32 v107, v107
	v_exp_f32_e32 v108, v108
	v_exp_f32_e32 v109, v109
	v_exp_f32_e32 v110, v110
	v_exp_f32_e32 v111, v111
	v_add_f32_e32 v0, v0, v104
	v_add_f32_e32 v15, v15, v105
	v_add_f32_e32 v0, v0, v106
	v_add_f32_e32 v15, v15, v107
	v_add_f32_e32 v0, v0, v108
	v_add_f32_e32 v15, v15, v109
	v_add_f32_e32 v0, v0, v110
	v_add_f32_e32 v15, v15, v111
	v_cvt_pk_bf16_f32 v100, v104, v105
	v_cvt_pk_bf16_f32 v101, v106, v107
	v_cvt_pk_bf16_f32 v102, v108, v109
	v_cvt_pk_bf16_f32 v103, v110, v111
	s_nop 1
	s_waitcnt lgkmcnt(6)
	v_mfma_f32_32x32x16_bf16 v[64:79], v[230:233], v[100:103], v[64:79]
	s_waitcnt lgkmcnt(4)
	v_mfma_f32_32x32x16_bf16 v[48:63], v[234:237], v[100:103], v[48:63]
	s_waitcnt lgkmcnt(2)
	v_mfma_f32_32x32x16_bf16 v[32:47], v[238:241], v[100:103], v[32:47]
	s_waitcnt lgkmcnt(0)
	v_mfma_f32_32x32x16_bf16 v[16:31], v[242:245], v[100:103], v[16:31]
	s_setprio 0
	v_add_f32_e32 v0, v0, v15
	v_add_f32_e32 v14, v14, v0

; DI unsigned cvt_pk_bf16(float lo, float hi) { unsigned r; asm volatile("v_cvt_pk_bf16_f32 %0, %1, %2" : "=v"(r) : "v"(lo), "v"(hi)); return r; }
; template <int DK>
; DI void attn_pass(const AttnSrc& s, const int q0, const float sc, LAS unsigned char* lds, f32x16 (&O)[4]) {
;     ...
; #pragma unroll
;         for (int j = 0; j < 16; ++j) { p0[j] = __builtin_amdgcn_exp2f(p0[j]); p1[j] = __builtin_amdgcn_exp2f(p1[j]); rs += p0[j] + p1[j]; }
;       } else {
;         const float cand = mx * sc;
;         const bool grow = cand > mrun + 8.f;
;         if (__builtin_amdgcn_ballot_w64(grow) != 0ull) {
;           const float mnew = grow ? cand : mrun;
;           const float alpha = __builtin_amdgcn_exp2f(mrun - mnew);
;           mrun = mnew; lrun *= alpha;
; #pragma unroll
;           for (int i = 0; i < 4; ++i)
; #pragma unroll
;             for (int j = 0; j < 16; ++j) O[i][j] *= alpha;
;         }
; #pragma unroll
;         for (int j = 0; j < 16; ++j) { p0[j] = __builtin_amdgcn_exp2f(p0[j] * sc - mrun); p1[j] = __builtin_amdgcn_exp2f(p1[j] * sc - mrun); rs += p0[j] + p1[j]; }
;       }
;       lrun += rs;
;       bf16x8 pb[4];
;       { u32x4 w;
;         w.x = cvt_pk_bf16(p0[0], p0[1]); w.y = cvt_pk_bf16(p0[2], p0[3]); w.z = cvt_pk_bf16(p0[4], p0[5]); w.w = cvt_pk_bf16(p0[6], p0[7]); pb[0] = __builtin_bit_cast(bf16x8, w);
;         w.x = cvt_pk_bf16(p0[8], p0[9]); w.y = cvt_pk_bf16(p0[10], p0[11]); w.z = cvt_pk_bf16(p0[12], p0[13]); w.w = cvt_pk_bf16(p0[14], p0[15]); pb[1] = __builtin_bit_cast(bf16x8, w);
;         w.x = cvt_pk_bf16(p1[0], p1[1]); w.y = cvt_pk_bf16(p1[2], p1[3]); w.z = cvt_pk_bf16(p1[4], p1[5]); w.w = cvt_pk_bf16(p1[6], p1[7]); pb[2] = __builtin_bit_cast(bf16x8, w);
;         w.x = cvt_pk_bf16(p1[8], p1[9]); w.y = cvt_pk_bf16(p1[10], p1[11]); w.z = cvt_pk_bf16(p1[12], p1[13]); w.w = cvt_pk_bf16(p1[14], p1[15]); pb[3] = __builtin_bit_cast(bf16x8, w); }
; #pragma unroll
;       for (int vt = 0; vt < 4; ++vt) {
;         if (vt + 1 < 4) vload(vt + 1, (vt + 1) & 1);
;         __builtin_amdgcn_s_setprio(1);
; #pragma unroll
;         for (int ks = 0; ks < 4; ++ks) O[vt] = __builtin_amdgcn_mfma_f32_32x32x16_bf16(vf[vt & 1][ks], pb[ks], O[vt], 0, 0, 0);
;         __builtin_amdgcn_s_setprio(0);
;       }
;     }
;     buf = (buf + 1 == NBUF) ? 0 : buf + 1; pbuf = (pbuf + 1 == NBUF) ? 0 : pbuf + 1;
.Lb64_end:
	s_add_i32 s18, s55, 1
	s_cmp_lg_u32 s18, 5
	s_cselect_b32 s55, s18, 0
	s_add_i32 s18, s58, 1
	s_cmp_lg_u32 s18, 5
	s_cselect_b32 s58, s18, 0
	s_add_u32 s14, s14, 0x60000
	s_addc_u32 s15, s15, 0
	s_add_i32 s53, s53, 64
	s_add_i32 s54, s54, 1
	s_add_i32 s57, s57, -1
	s_cmp_lg_u32 s42, s14
	s_cbranch_scc1 .Lb64_loop
	s_sub_i32 s18, s53, 0x7f
	s_cmp_gt_i32 s18, s56
	s_cbranch_scc1 .LBB0_117
	ds_read_b64_tr_b16 v[230:231], v246 offset:12288
	ds_read_b64_tr_b16 v[232:233], v246 offset:14336
	ds_read_b64_tr_b16 v[234:235], v247 offset:12288
	ds_read_b64_tr_b16 v[236:237], v247 offset:14336
	ds_read_b64_tr_b16 v[238:239], v248 offset:12288
	ds_read_b64_tr_b16 v[240:241], v248 offset:14336
	ds_read_b64_tr_b16 v[242:243], v249 offset:12288
	ds_read_b64_tr_b16 v[244:245], v249 offset:14336
	s_setprio 1
	s_waitcnt lgkmcnt(14)
	v_mfma_f32_32x32x16_bf16 v[64:79], v[2:5], v[112:115], v[64:79]
	s_waitcnt lgkmcnt(12)
	v_mfma_f32_32x32x16_bf16 v[48:63], v[6:9], v[112:115], v[48:63]
	s_waitcnt lgkmcnt(10)
	v_mfma_f32_32x32x16_bf16 v[32:47], v[10:13], v[112:115], v[32:47]
	s_waitcnt lgkmcnt(8)
	v_mfma_f32_32x32x16_bf16 v[16:31], v[144:147], v[112:115], v[16:31]
	v_exp_f32_e32 v120, v120
	v_exp_f32_e32 v121, v121
	v_exp_f32_e32 v122, v122
	v_exp_f32_e32 v123, v123
	v_exp_f32_e32 v124, v124
	v_exp_f32_e32 v125, v125
	v_exp_f32_e32 v126, v126
	v_exp_f32_e32 v127, v127
	v_add_f32_e32 v0, v0, v120
	v_add_f32_e32 v15, v15, v121
	v_add_f32_e32 v0, v0, v122
	v_add_f32_e32 v15, v15, v123
	v_add_f32_e32 v0, v0, v124
	v_add_f32_e32 v15, v15, v125
	v_add_f32_e32 v0, v0, v126
	v_add_f32_e32 v15, v15, v127
	v_cvt_pk_bf16_f32 v116, v120, v121
	v_cvt_pk_bf16_f32 v117, v122, v123
	v_cvt_pk_bf16_f32 v118, v124, v125
	v_cvt_pk_bf16_f32 v119, v126, v127
	ds_read_b64_tr_b16 v[2:3], v246 offset:16384
	ds_read_b64_tr_b16 v[4:5], v246 offset:18432
	ds_read_b64_tr_b16 v[6:7], v247 offset:16384
	ds_read_b64_tr_b16 v[8:9], v247 offset:18432
	ds_read_b64_tr_b16 v[10:11], v248 offset:16384
	ds_read_b64_tr_b16 v[12:13], v248 offset:18432
	ds_read_b64_tr_b16 v[144:145], v249 offset:16384
	ds_read_b64_tr_b16 v[146:147], v249 offset:18432
	s_waitcnt lgkmcnt(14)
	v_mfma_f32_32x32x16_bf16 v[64:79], v[230:233], v[116:119], v[64:79]
	s_waitcnt lgkmcnt(12)
	v_mfma_f32_32x32x16_bf16 v[48:63], v[234:237], v[116:119], v[48:63]
	s_waitcnt lgkmcnt(10)
	v_mfma_f32_32x32x16_bf16 v[32:47], v[238:241], v[116:119], v[32:47]
	s_waitcnt lgkmcnt(8)
	v_mfma_f32_32x32x16_bf16 v[16:31], v[242:245], v[116:119], v[16:31]
	v_exp_f32_e32 v96, v96
	v_exp_f32_e32 v97, v97
	v_exp_f32_e32 v98, v98
	v_exp_f32_e32 v99, v99
	v_exp_f32_e32 v100, v100
	v_exp_f32_e32 v101, v101
	v_exp_f32_e32 v102, v102
	v_exp_f32_e32 v103, v103
	v_add_f32_e32 v0, v0, v96
	v_add_f32_e32 v15, v15, v97
	v_add_f32_e32 v0, v0, v98
	v_add_f32_e32 v15, v15, v99
	v_add_f32_e32 v0, v0, v100
	v_add_f32_e32 v15, v15, v101
	v_add_f32_e32 v0, v0, v102
	v_add_f32_e32 v15, v15, v103
	v_cvt_pk_bf16_f32 v96, v96, v97
	v_cvt_pk_bf16_f32 v97, v98, v99
	v_cvt_pk_bf16_f32 v98, v100, v101
	v_cvt_pk_bf16_f32 v99, v102, v103
	ds_read_b64_tr_b16 v[230:231], v246 offset:20480
	ds_read_b64_tr_b16 v[232:233], v246 offset:22528
	ds_read_b64_tr_b16 v[234:235], v247 offset:20480
	ds_read_b64_tr_b16 v[236:237], v247 offset:22528
	ds_read_b64_tr_b16 v[238:239], v248 offset:20480
	ds_read_b64_tr_b16 v[240:241], v248 offset:22528
	ds_read_b64_tr_b16 v[242:243], v249 offset:20480
	ds_read_b64_tr_b16 v[244:245], v249 offset:22528
	s_waitcnt lgkmcnt(14)
	v_mfma_f32_32x32x16_bf16 v[64:79], v[2:5], v[96:99], v[64:79]
	s_waitcnt lgkmcnt(12)
	v_mfma_f32_32x32x16_bf16 v[48:63], v[6:9], v[96:99], v[48:63]
	s_waitcnt lgkmcnt(10)
	v_mfma_f32_32x32x16_bf16 v[32:47], v[10:13], v[96:99], v[32:47]
	s_waitcnt lgkmcnt(8)
	v_mfma_f32_32x32x16_bf16 v[16:31], v[144:147], v[96:99], v[16:31]
	v_exp_f32_e32 v104, v104
	v_exp_f32_e32 v105, v105
	v_exp_f32_e32 v106, v106
	v_exp_f32_e32 v107, v107
	v_exp_f32_e32 v108, v108
	v_exp_f32_e32 v109, v109
	v_exp_f32_e32 v110, v110
	v_exp_f32_e32 v111, v111
	v_add_f32_e32 v0, v0, v104
	v_add_f32_e32 v15, v15, v105
	v_add_f32_e32 v0, v0, v106
	v_add_f32_e32 v15, v15, v107
	v_add_f32_e32 v0, v0, v108
	v_add_f32_e32 v15, v15, v109
	v_add_f32_e32 v0, v0, v110
	v_add_f32_e32 v15, v15, v111
	v_cvt_pk_bf16_f32 v100, v104, v105
	v_cvt_pk_bf16_f32 v101, v106, v107
	v_cvt_pk_bf16_f32 v102, v108, v109
	v_cvt_pk_bf16_f32 v103, v110, v111
	s_nop 1
	s_waitcnt lgkmcnt(6)
	v_mfma_f32_32x32x16_bf16 v[64:79], v[230:233], v[100:103], v[64:79]
	s_waitcnt lgkmcnt(4)
	v_mfma_f32_32x32x16_bf16 v[48:63], v[234:237], v[100:103], v[48:63]
	s_waitcnt lgkmcnt(2)
	v_mfma_f32_32x32x16_bf16 v[32:47], v[238:241], v[100:103], v[32:47]
	s_waitcnt lgkmcnt(0)
	v_mfma_f32_32x32x16_bf16 v[16:31], v[242:245], v[100:103], v[16:31]
	s_setprio 0
	v_add_f32_e32 v0, v0, v15
	v_add_f32_e32 v14, v14, v0
	s_branch .LBB0_117
